# prologue overlap variant: 6144 weight items per recurrence phase moved to the streamer workgroups (was 8192)
# speedup vs baseline: 1.0083x; 1.0048x over previous
; #define LAS __attribute__((address_space(3)))
; __global__ void __launch_bounds__(NTHR, 2) mega(const Args a) {
;     extern __shared__ __attribute__((aligned(16))) unsigned char lds_raw[];
;     LAS unsigned char* lds = (LAS unsigned char*)lds_raw;
;     const int wg0 = blockIdx.x, nwg0 = gridDim.x, tid = threadIdx.x;
;     for (int u = tid; u < (LDS_BYTES - LDSCTL_OFF) / 4; u += NTHR) ((LAS unsigned*)(lds + LDSCTL_OFF))[u] = 0u;
;     __syncthreads();
;     if (tid == 0) { const unsigned long long* src = (const unsigned long long*)&a.p;
; #pragma unroll
;         for (int i = 0; i < 25; ++i) *(LAS unsigned long long*)(lds + LDS_P_OFF + 8 * i) = src[i]; }
;     __syncthreads();
_Z4mega4Args:
	v_mov_b32_e32 v250, 0
	s_mov_b32 s3, 0x1cb00
	v_writelane_b32 v250, s3, 2
	s_mov_b32 s3, 0x1caff
	v_writelane_b32 v250, s3, 3
	s_add_u32 s4, s0, 0xd0
	s_addc_u32 s5, s1, 0
	s_movk_i32 s3, 0x200
	v_writelane_b32 v249, s4, 0
	v_cmp_gt_u32_e32 vcc, s3, v0
	s_nop 0
	v_writelane_b32 v249, s5, 1
	s_and_saveexec_b64 s[6:7], vcc
	v_lshl_add_u32 v1, v0, 2, 0
	v_add_u32_e32 v1, 0x23800, v1
	v_mov_b32_e32 v2, 0
	ds_write_b32 v1, v2
	s_or_b64 exec, exec, s[6:7]
	s_waitcnt lgkmcnt(0)
	s_barrier
	v_cmp_eq_u32_e64 s[4:5], 0, v0
	s_mov_b64 s[22:23], exec
	s_nop 0
	v_writelane_b32 v249, s4, 2
	s_nop 1
	v_writelane_b32 v249, s5, 3
	s_and_b64 s[4:5], s[22:23], s[4:5]
	s_mov_b64 exec, s[4:5]
	s_cbranch_execz .LBB0_4
	s_load_dwordx16 s[4:19], s[0:1], 0x0
	s_add_i32 s20, 0, 0x23900
	s_load_dwordx16 s[48:63], s[0:1], 0x40
	v_mov_b32_e32 v1, s20
	s_add_i32 s20, 0, 0x23970
	s_waitcnt lgkmcnt(0)
	v_mov_b32_e32 v2, s4
	v_mov_b32_e32 v3, s5
	v_mov_b32_e32 v4, s6
	v_mov_b32_e32 v5, s7
	s_add_i32 s4, 0, 0x23910
	ds_write_b128 v1, v[2:5]
	v_mov_b32_e32 v2, s8
	v_mov_b32_e32 v3, s9
	v_mov_b32_e32 v4, s10
	v_mov_b32_e32 v5, s11
	v_mov_b32_e32 v1, s4
	s_add_i32 s4, 0, 0x23920
	ds_write_b128 v1, v[2:5]
	v_mov_b32_e32 v2, s12
	v_mov_b32_e32 v3, s13
	v_mov_b32_e32 v4, s14
	v_mov_b32_e32 v5, s15
	v_mov_b32_e32 v1, s4
	s_add_i32 s4, 0, 0x23930
	ds_write_b128 v1, v[2:5]
	v_mov_b32_e32 v2, s16
	v_mov_b32_e32 v3, s17
	v_mov_b32_e32 v4, s18
	v_mov_b32_e32 v5, s19
	v_mov_b32_e32 v1, s4
	s_add_i32 s4, 0, 0x23940
	ds_write_b128 v1, v[2:5]
	v_mov_b32_e32 v2, s48
	v_mov_b32_e32 v3, s49
	v_mov_b32_e32 v4, s50
	v_mov_b32_e32 v5, s51
	v_mov_b32_e32 v1, s4
	s_add_i32 s4, 0, 0x23950
	ds_write_b128 v1, v[2:5]
	v_mov_b32_e32 v2, s52
	v_mov_b32_e32 v3, s53
	v_mov_b32_e32 v4, s54
	v_mov_b32_e32 v5, s55
	v_mov_b32_e32 v1, s4
	s_add_i32 s4, 0, 0x23960
	ds_write_b128 v1, v[2:5]
	v_mov_b32_e32 v1, s4
	s_load_dwordx16 s[4:19], s[0:1], 0x80
	v_mov_b32_e32 v2, s56
	v_mov_b32_e32 v3, s57
	v_mov_b32_e32 v4, s58
	v_mov_b32_e32 v5, s59
	ds_write_b128 v1, v[2:5]
	v_mov_b32_e32 v2, s60
	v_mov_b32_e32 v3, s61
	v_mov_b32_e32 v4, s62
	v_mov_b32_e32 v5, s63
	v_mov_b32_e32 v1, s20
	ds_write_b128 v1, v[2:5]
	s_waitcnt lgkmcnt(0)
	v_mov_b32_e32 v2, s4
	s_add_i32 s4, 0, 0x23980
	v_mov_b32_e32 v3, s5
	v_mov_b32_e32 v4, s6
	v_mov_b32_e32 v5, s7
	v_mov_b32_e32 v1, s4
	s_add_i32 s4, 0, 0x23990
	ds_write_b128 v1, v[2:5]
	v_mov_b32_e32 v2, s8
	v_mov_b32_e32 v3, s9
	v_mov_b32_e32 v4, s10
	v_mov_b32_e32 v5, s11
	v_mov_b32_e32 v1, s4
	s_add_i32 s4, 0, 0x239a0
	ds_write_b128 v1, v[2:5]
	v_mov_b32_e32 v1, s4
	s_load_dwordx2 s[4:5], s[0:1], 0xc0
	v_mov_b32_e32 v2, s12
	v_mov_b32_e32 v3, s13
	v_mov_b32_e32 v4, s14
	v_mov_b32_e32 v5, s15
	s_add_i32 s6, 0, 0x239b0
	ds_write_b128 v1, v[2:5]
	v_mov_b32_e32 v2, s16
	v_mov_b32_e32 v3, s17
	v_mov_b32_e32 v4, s18
	v_mov_b32_e32 v5, s19
	v_mov_b32_e32 v1, s6
	s_add_i32 s6, 0, 0x239c0
	ds_write_b128 v1, v[2:5]
	v_mov_b32_e32 v1, s6
	s_waitcnt lgkmcnt(0)
	v_mov_b64_e32 v[2:3], s[4:5]
	ds_write_b64 v1, v[2:3]

; #define LAS __attribute__((address_space(3)))
; __device__ __forceinline__ void phase_prologue(const P& p, unsigned char* ws, LAS unsigned char* lds, int wg, int nwg) {
;     ...
;     for (int it = gw; it < DEPTH * I_LAYER; it += NGW) {
; __device__ __forceinline__ void phase_rec(const P& p, unsigned char* ws, int l, LAS unsigned char* lds, int wg, int nwg) {
;     int lrank = wg, nloop = nwg, srank = wg, nstr = nwg;
;     const bool split = nwg >= 16;
;     if (split) { const int grp = wg >> 3, ngrp = (nwg + 7) >> 3, nlg = (ngrp + 1) >> 1;
;         const int full_l = nlg * 8 - ((ngrp & 1) ? (ngrp * 8 - nwg) : 0), full_s = nwg - full_l;
;         nloop = full_l; nstr = full_s; lrank = (grp >> 1) * 8 + (wg & 7); srank = (grp >> 1) * 8 + (wg & 7);
;         if (grp & 1) lrank = 1 << 30; else srank = 1 << 30; }
;     for (int rl = 0; rl < REP_LOOP; ++rl) for (int tk = lrank; tk < 128; tk += nloop) rec_loop_task(p, ws, l, lds, tk);
;     const int nlk = split ? LK_ITEMS * nloop : 0;
;     for (int rs = 0; rs < REP_SST; ++rs) {
;     if (split) for (int it = lrank; it < nlk; it += nloop) rec_sample_item<HV, false>(p, ws, l, lds, it >> 3, it & 7);
;     for (int it = nlk + srank; it < DECB * HH; it += nstr) rec_sample_item<HV, false>(p, ws, l, lds, it >> 3, it & 7);
;     for (int it = srank; it < DECB * GH; it += nstr) rec_sample_item<GV, true>(p, ws, l, lds, it >> 2, it & 3); }
; }
.LBB0_1145:
	v_readlane_b32 s0, v248, 27
	s_cmp_gt_u32 s0, 2
	s_cbranch_scc1 .Lcv_skip
	v_readlane_b32 s1, v248, 19
	s_bitcmp1_b32 s1, 3
	s_cbranch_scc0 .Lcv_skip
	s_waitcnt lgkmcnt(0)
	s_barrier
	v_writelane_b32 v251, s3, 0
	v_writelane_b32 v251, s4, 1
	v_writelane_b32 v251, s5, 2
	v_writelane_b32 v251, s6, 3
	v_writelane_b32 v251, s7, 4
	v_writelane_b32 v251, s8, 5
	v_writelane_b32 v251, s9, 6
	v_writelane_b32 v251, s10, 7
	v_writelane_b32 v251, s11, 8
	v_writelane_b32 v251, s12, 9
	v_writelane_b32 v251, s13, 10
	v_writelane_b32 v251, s14, 11
	v_writelane_b32 v251, s15, 12
	v_writelane_b32 v251, s16, 13
	v_writelane_b32 v251, s17, 14
	v_writelane_b32 v251, s18, 15
	v_writelane_b32 v251, s19, 16
	v_writelane_b32 v251, s20, 17
	v_writelane_b32 v251, s21, 18
	v_writelane_b32 v251, s23, 20
	v_writelane_b32 v251, s24, 21
	v_writelane_b32 v251, s25, 22
	v_writelane_b32 v251, s26, 23
	v_writelane_b32 v251, s27, 24
	v_writelane_b32 v251, s28, 25
	v_writelane_b32 v251, s29, 26
	v_writelane_b32 v251, s30, 27
	v_writelane_b32 v251, s31, 28
	v_writelane_b32 v251, s32, 29
	v_writelane_b32 v251, s33, 30
	v_writelane_b32 v251, s34, 31
	v_writelane_b32 v251, s35, 32
	v_writelane_b32 v251, s36, 33
	v_writelane_b32 v251, s37, 34
	v_writelane_b32 v251, s38, 35
	v_writelane_b32 v251, s39, 36
	v_writelane_b32 v251, s40, 37
	v_writelane_b32 v251, s41, 38
	v_writelane_b32 v251, s42, 39
	v_writelane_b32 v251, s43, 40
	v_writelane_b32 v251, s44, 41
	v_writelane_b32 v251, s45, 42
	v_writelane_b32 v251, s46, 43
	v_writelane_b32 v251, s47, 44
	v_writelane_b32 v251, s48, 45
	v_writelane_b32 v251, s49, 46
	v_writelane_b32 v251, s50, 47
	v_writelane_b32 v251, s51, 48
	v_writelane_b32 v251, s52, 49
	v_writelane_b32 v251, s53, 50
	v_writelane_b32 v251, s54, 51
	v_writelane_b32 v251, s55, 52
	v_writelane_b32 v251, s56, 53
	v_writelane_b32 v251, s57, 54
	v_writelane_b32 v251, s58, 55
	v_writelane_b32 v251, s59, 56
	v_writelane_b32 v251, s60, 57
	v_writelane_b32 v251, s61, 58
	v_writelane_b32 v251, s62, 59
	v_writelane_b32 v251, s63, 60
	v_writelane_b32 v251, s64, 61
	v_writelane_b32 v251, s65, 62
	v_writelane_b32 v251, s66, 63
	v_writelane_b32 v252, s67, 0
	v_writelane_b32 v252, s68, 1
	v_writelane_b32 v252, s69, 2
	v_writelane_b32 v252, s70, 3
	v_writelane_b32 v252, s71, 4
	v_writelane_b32 v252, s72, 5
	v_writelane_b32 v252, s73, 6
	v_writelane_b32 v252, s74, 7
	v_writelane_b32 v252, s75, 8
	v_writelane_b32 v252, s76, 9
	v_writelane_b32 v252, s77, 10
	v_writelane_b32 v252, s78, 11
	v_writelane_b32 v252, s79, 12
	v_writelane_b32 v252, s80, 13
	v_writelane_b32 v252, s81, 14
	v_writelane_b32 v252, s82, 15
	v_writelane_b32 v252, s83, 16
	v_writelane_b32 v252, s84, 17
	v_writelane_b32 v252, s85, 18
	v_writelane_b32 v252, s86, 19
	v_writelane_b32 v252, s87, 20
	v_writelane_b32 v252, s88, 21
	v_writelane_b32 v252, s89, 22
	v_writelane_b32 v252, s90, 23
	v_writelane_b32 v252, s91, 24
	v_writelane_b32 v252, s92, 25
	v_writelane_b32 v252, s93, 26
	v_writelane_b32 v252, s94, 27
	v_writelane_b32 v252, s95, 28
	v_writelane_b32 v252, s96, 29
	v_writelane_b32 v252, s97, 30
	v_writelane_b32 v252, s98, 31
	v_writelane_b32 v252, s99, 32
	v_mov_b32_e32 v253, v1
	s_lshr_b32 s22, s1, 4
	s_lshl_b32 s22, s22, 3
	s_and_b32 s1, s1, 7
	s_or_b32 s1, s22, s1
	v_writelane_b32 v250, s1, 4
	s_mul_i32 s22, s0, 0x1800
	s_add_i32 s22, s22, 0x1cb00
	v_writelane_b32 v250, s22, 1
	s_add_i32 s22, s22, 0x1800
	v_writelane_b32 v250, s22, 2
	s_add_i32 s22, s22, -1
	v_writelane_b32 v250, s22, 3
	s_mov_b32 s22, 1
	v_writelane_b32 v250, s22, 0
	s_branch .Lcv_entry
